# scan: physical waves 5 and 6 swap virtual wave ids so the two k/kk/v step-vector waves sit on SIMD1 and SIMD3 (one per LDS store-path half)
# baseline (speedup 1.0000x reference)
; #define opaque_tid() opaque_tid_w(wid_u)
; __device__ __forceinline__ void scan_phase(PREF p, char* smem, const int wid_u) {
;     ...
;   const int tid = opaque_tid();
;   const int wave = __builtin_amdgcn_readfirstlane(tid >> 6), lane = tid & 63, fr = lane & 15, fq = lane >> 4;
;   const int item = blockIdx.x;
;   if (item < 256) {
;     const int s = item < 128 ? 8 + (item >> 4) : ((item - 128) >> 4);
;     const int h = (item & 15) >> 1, d = item & 1;
;     const int T = s < 8 ? 4096 : 8192, r0seq = seq_start(s), nch = T / 32;
;     bf16_t* yout = P_RY + (size_t)d * NTOK * 512;
;     {
;       const int g = tid >> 6, k = tid & 63;
;       const float muk = p.shift_mu[1024 - 512 + h * 64 + k], mur = p.shift_mu[512 - 512 + h * 64 + k], muv = p.shift_mu[1536 - 512 + h * 64 + k];
;       float v;
;       if (g == 0) v = 0.5f * muk;
;       else if (g == 1) v = 0.5f * mur;
;       else if (g == 2) v = 1.f - muk;
;       else if (g == 3) v = 1.f - mur;
;       else if (g == 4) v = 1.f - muv;
;       else if (g == 5) v = p.k_k[h * 64 + k];
;       else if (g == 6) v = p.k_a[h * 64 + k];
;       else v = p.r_k[h * 64 + k];
;       cst[g * 64 + k] = v;
;       if (g == 0) cst[8 * 64 + k] = 0.5f * muv;
;       for (int i = tid; i < 2 * 64 * 72 / 2; i += NTHR) ((unsigned*)Sbf)[i] = 0u;
.LBB0_482:
	s_or_b64 exec, exec, s[2:3]
	s_mov_b64 s[52:53], s[0:1]
	s_waitcnt lgkmcnt(0)
	s_barrier
	s_cmp_eq_u32 s84, 0x140
	s_cselect_b32 s98, 0x180, s84
	s_cmp_eq_u32 s84, 0x180
	s_cselect_b32 s84, 0x140, s98
	s_cmp_eq_u32 s66, 5
	s_cselect_b32 s98, 6, s66
	s_cmp_eq_u32 s66, 6
	s_cselect_b32 s66, 5, s98
	s_load_dwordx2 s[48:49], s[52:53], 0x110
	v_mbcnt_lo_u32_b32 v75, -1, 0
	v_mbcnt_hi_u32_b32 v75, -1, v75
	s_waitcnt lgkmcnt(0)
	s_add_u32 s50, s48, 0x1ae90000
	v_add_u32_e32 v146, s84, v75
	s_addc_u32 s51, s49, 0
	v_ashrrev_i32_e32 v5, 6, v146
	s_cmpk_gt_i32 s33, 0xff
	v_readfirstlane_b32 s90, v5
	s_cbranch_scc1 .LBB0_604
	s_load_dwordx2 s[2:3], s[52:53], 0x70
	s_bfe_u32 s24, s33, 0x30001
	v_and_b32_e32 v88, 63, v75
	s_lshl_b32 s89, s24, 6
	v_or_b32_e32 v0, s89, v88
	v_mov_b32_e32 v1, 0
	v_lshlrev_b32_e32 v0, 2, v0
	s_waitcnt lgkmcnt(0)
	v_lshl_add_u64 v[2:3], s[2:3], 0, v[0:1]
	v_add_co_u32_e32 v8, vcc, 0x1000, v2
	s_nop 1
	v_addc_co_u32_e32 v9, vcc, 0, v3, vcc
	global_load_dword v7, v0, s[2:3] offset:2048
	global_load_dword v1, v[8:9], off
	v_cmp_gt_u32_e32 vcc, 64, v146
	v_cmp_lt_u32_e64 s[2:3], 63, v146
	s_and_saveexec_b64 s[4:5], s[2:3]
	s_xor_b64 s[4:5], exec, s[4:5]
	s_cbranch_execz .LBB0_490
	v_cmp_lt_i32_e64 s[2:3], 3, v5
	s_mov_b64 s[6:7], 0
	s_mov_b64 s[8:9], 0
	s_and_saveexec_b64 s[10:11], s[2:3]
	s_xor_b64 s[10:11], exec, s[10:11]
	s_cbranch_execnz .LBB0_779
	s_or_saveexec_b64 s[10:11], s[10:11]
	s_xor_b64 exec, exec, s[10:11]
	s_cbranch_execnz .LBB0_790

; __device__ __forceinline__ void pool_tile(const bf16_t* __restrict__ z, bf16_t* __restrict__ mo, int tile, int tid) {
;   const int row0 = tile * 32;
;   int s, t0, T;
;   row_seq(row0, s, t0, T);
;   const int oc = tid >> 3, seg = tid & 7, c0 = oc * 8, grp = __builtin_amdgcn_readfirstlane(oc >> 4);
;   const int rb = row0 + seg * 4, tb = t0 + seg * 4;
; __device__ __forceinline__ void scan_phase(PREF p, char* smem, const int wid_u) {
;     ...
;   if (item >= 128) {
;     const int nb = gridDim.x - 128;
;     for (int tile = item - 128; tile < NTOK / 32; tile += nb) pool_tile(z, P_RH, tile, tid);
.LBB0_604:
	s_cmp_eq_u32 s84, 0x140
	s_cselect_b32 s98, 0x180, s84
	s_cmp_eq_u32 s84, 0x180
	s_cselect_b32 s84, 0x140, s98
	s_cmpk_lt_i32 s33, 0x80
	s_cbranch_scc1 .LBB0_751
	s_add_i32 s13, s42, 0xffffff80
	s_add_i32 s15, s33, 0xffffff80
	s_cmpk_gt_u32 s33, 0xc7f
	s_cbranch_scc1 .LBB0_706
	v_and_b32_e32 v0, -8, v146
	v_lshlrev_b32_e32 v1, 2, v75
	v_and_b32_e32 v147, 28, v1
	v_ashrrev_i32_e32 v1, 31, v0
	v_lshlrev_b64 v[0:1], 1, v[0:1]
	v_lshl_add_u64 v[76:77], s[50:51], 0, v[0:1]
	v_lshl_add_u64 v[0:1], s[48:49], 0, v[0:1]
	s_mov_b64 s[2:3], 0x2e90000
	s_lshl_b32 s9, s42, 5
	v_lshl_add_u64 v[78:79], v[0:1], 0, s[2:3]
	s_lshl_b32 s8, s33, 5
	s_addk_i32 s9, 0xf000
	s_movk_i32 s10, 0xfe0
	s_movk_i32 s11, 0x1000
	s_movk_i32 s12, 0x1400
	s_mov_b32 s14, s15
	s_branch .LBB0_609
